# v10
# speedup vs baseline: 1.0025x; 1.0025x over previous
; #define LAS __attribute__((address_space(3)))
; #define MFMA32(a, b, c) __builtin_amdgcn_mfma_f32_32x32x16_bf16((a), (b), (c), 0, 0, 0)
; DI void attn_step(const LAS unsigned char* Kb, const LAS unsigned char* Vb, f32x16& c0, f32x16& c1, f32x16& n0, f32x16& n1, bf16x8 (&pf)[2][2],
;                   f32x16 (&o)[4], f32x16& negm, float& mrun, float& lrun, const bf16x8 (&qf)[4]) {
;     ...
;     vf[0] = AT_VF(0); vf[1] = AT_VF(1); vf[2] = AT_VF(2);
; DI void attn_unit(LAS unsigned char* lds, const bf16_t* QK, const bf16_t* VT, bf16_t* O, int mp, int h, int q0, int kt0, int kt1, int coff, int wid0) {
;     ...
;     f32x16 o[4], negm;
; #pragma unroll
;     for (int r = 0; r < 16; ++r) { negm[r] = 0.f;
; #pragma unroll
;         for (int d = 0; d < 4; ++d) o[d][r] = 0.f; }
;     float mrun = 0.f, lrun = 0.f;
;     bf16x8 pf[2][2];
; #pragma unroll
;     for (int a = 0; a < 2; ++a)
; #pragma unroll
;         for (int b = 0; b < 2; ++b)
; #pragma unroll
;             for (int j = 0; j < 8; ++j) pf[a][b][j] = 0;
;     __syncthreads();
;     f32x16 sa0, sa1, sb0, sb1;
; #pragma unroll
;     for (int r = 0; r < 16; ++r) { sa0[r] = 0.f; sa1[r] = 0.f; }
; #pragma unroll
;     for (int ks = 0; ks < 4; ++ks) {
;         const bf16x8 k0 = *(const LAS bf16x8*)(lds + koff + ks * 32), k1 = *(const LAS bf16x8*)(lds + koff + 32 * KP * 2 + ks * 32);
;         sa0 = MFMA32(k0, qf[ks], sa0); sa1 = MFMA32(k1, qf[ks], sa1);
;     }
.LBB0_456:
	s_or_b64 exec, exec, s[8:9]
	s_movk_i32 s5, 0x48
	v_mad_u32_u24 v4, v4, s5, v7
	v_lshl_add_u32 v196, v4, 1, 0
	s_waitcnt lgkmcnt(0)
	s_barrier
	ds_read_b128 v[8:11], v196
	ds_read_b128 v[12:15], v196 offset:32
	s_waitcnt lgkmcnt(1)
	v_mfma_f32_32x32x16_bf16 v[96:111], v[8:11], v[128:131], 0
	ds_read_b128 v[8:11], v196 offset:4608
	v_readlane_b32 s8, v253, 56
	v_readlane_b32 s9, v253, 57
	v_add_u32_e32 v2, s4, v2
	s_mov_b32 s5, 0x8400
	v_mov_b64_e32 v[4:5], s[8:9]
	v_mad_i64_i32 v[4:5], s[8:9], v2, s5, v[4:5]
	v_and_b32_e32 v2, 48, v3
	v_add_u32_e32 v1, v1, v2
	v_and_or_b32 v1, v6, 4, v1
	ds_read_b128 v[16:19], v196 offset:4640
	v_lshlrev_b32_e32 v28, 1, v1
	v_mov_b32_e32 v1, v185
	v_lshl_add_u64 v[190:191], v[4:5], 0, v[0:1]
	ds_read_b128 v[0:3], v196 offset:64
	s_waitcnt lgkmcnt(2)
	v_mfma_f32_32x32x16_bf16 v[64:79], v[8:11], v[128:131], 0
	s_mov_b32 s68, 0
	s_mov_b32 s69, s68
	s_mov_b32 s70, s68
	s_mov_b32 s71, s68
	s_mov_b32 s72, s68
	s_mov_b32 s73, s68
	s_mov_b32 s74, s68
	v_mfma_f32_32x32x16_bf16 v[96:111], v[12:15], v[132:135], v[96:111]
	s_mov_b32 s75, s68
	s_mov_b32 s76, s68
	s_mov_b32 s77, s68
	s_mov_b32 s78, s68
	s_mov_b32 s79, s68
	s_mov_b32 s80, s68
	s_mov_b32 s81, s68
	s_waitcnt lgkmcnt(1)
	v_mfma_f32_32x32x16_bf16 v[64:79], v[16:19], v[132:135], v[64:79]
	ds_read_b128 v[16:19], v196 offset:4672
	ds_read_b128 v[20:23], v196 offset:96
	ds_read_b128 v[24:27], v196 offset:4704
	s_mov_b32 s82, s68
	s_mov_b32 s83, s68
	v_mov_b32_e32 v221, 0
	v_add_u32_e32 v197, 0, v28
	v_add_u32_e32 v244, 0x4800, v197
	v_add_u32_e32 v245, 0x6800, v197
	v_add_u32_e32 v246, 0x9000, v197
	v_add_u32_e32 v247, 0xb000, v197
	v_lshl_add_u64 v[192:193], v[190:191], 0, s[84:85]
	s_waitcnt lgkmcnt(3)
	v_mfma_f32_32x32x16_bf16 v[96:111], v[0:3], v[136:139], v[96:111]
	v_mov_b64_e32 v[0:1], s[68:69]
	v_mov_b64_e32 v[14:15], s[82:83]
	v_mov_b64_e32 v[2:3], s[70:71]
	v_mov_b64_e32 v[4:5], s[72:73]
	v_mov_b64_e32 v[6:7], s[74:75]
	v_mov_b64_e32 v[8:9], s[76:77]
	v_mov_b64_e32 v[10:11], s[78:79]
	s_waitcnt lgkmcnt(2)
	v_mfma_f32_32x32x16_bf16 v[64:79], v[16:19], v[136:139], v[64:79]
	v_mov_b64_e32 v[12:13], s[80:81]
	v_mov_b64_e32 v[46:47], v[14:15]
	v_mov_b64_e32 v[62:63], v[14:15]
	v_mov_b32_e32 v156, 0
	v_mov_b32_e32 v157, 0
	v_mov_b32_e32 v158, 0
	v_mov_b32_e32 v159, 0
	s_waitcnt lgkmcnt(1)
	v_mfma_f32_32x32x16_bf16 v[96:111], v[20:23], v[140:143], v[96:111]
	v_mov_b32_e32 v152, 0
	v_mov_b32_e32 v153, 0
	v_mov_b32_e32 v154, 0
	v_mov_b32_e32 v155, 0
	v_mov_b32_e32 v144, 0
	v_mov_b32_e32 v145, 0
	v_mov_b32_e32 v146, 0
	s_waitcnt lgkmcnt(0)
	v_mfma_f32_32x32x16_bf16 v[64:79], v[24:27], v[140:143], v[64:79]
	v_mov_b64_e32 v[30:31], v[14:15]
	v_mov_b32_e32 v147, 0
	v_mov_b32_e32 v148, 0
	v_mov_b32_e32 v149, 0
	v_mov_b32_e32 v150, 0
	v_mov_b32_e32 v151, 0
	v_mov_b64_e32 v[28:29], v[12:13]
	v_mov_b64_e32 v[26:27], v[10:11]
	v_mov_b64_e32 v[24:25], v[8:9]
	v_mov_b64_e32 v[22:23], v[6:7]
	v_mov_b64_e32 v[20:21], v[4:5]
	v_mov_b64_e32 v[18:19], v[2:3]
	v_mov_b64_e32 v[16:17], v[0:1]
	v_mov_b64_e32 v[44:45], v[12:13]
	v_mov_b64_e32 v[42:43], v[10:11]
	v_mov_b64_e32 v[40:41], v[8:9]
	v_mov_b64_e32 v[38:39], v[6:7]
	v_mov_b64_e32 v[36:37], v[4:5]
	v_mov_b64_e32 v[34:35], v[2:3]
	v_mov_b64_e32 v[32:33], v[0:1]
	v_mov_b64_e32 v[60:61], v[12:13]
	v_mov_b64_e32 v[58:59], v[10:11]
	v_mov_b64_e32 v[56:57], v[8:9]
	v_mov_b64_e32 v[54:55], v[6:7]
	v_mov_b64_e32 v[52:53], v[4:5]
	v_mov_b64_e32 v[50:51], v[2:3]
	v_mov_b64_e32 v[48:49], v[0:1]
	v_mov_b32_e32 v198, 0
	v_mov_b32_e32 v112, 0
	v_mov_b32_e32 v113, v221
	v_mov_b32_e32 v114, v221
	v_mov_b32_e32 v115, v221
	v_mov_b32_e32 v116, v221
	v_mov_b32_e32 v117, v221
	v_mov_b32_e32 v118, v221
	v_mov_b32_e32 v119, v221
	v_mov_b32_e32 v120, v221
	v_mov_b32_e32 v121, v221
	v_mov_b32_e32 v122, v221
	v_mov_b32_e32 v123, v221
	v_mov_b32_e32 v124, v221
	v_mov_b32_e32 v125, v221
	v_mov_b32_e32 v126, v221
	v_mov_b32_e32 v127, v221
	v_mov_b32_e32 v194, 1.0
	v_cmp_lt_u32_e32 vcc, 0xff, v199
	s_nop 1
	s_cmp_lg_u64 vcc, 0
	s_cbranch_scc0 .LBB0_457
	ds_read_b128 v[172:175], v196 offset:36864
	ds_read_b128 v[176:179], v196 offset:36896
	ds_read_b128 v[180:183], v196 offset:36928
	ds_read_b128 v[88:91], v196 offset:36960
	s_branch .Lg1_457
	.p2align 6

; DI void attn_step(const LAS unsigned char* Kb, const LAS unsigned char* Vb, f32x16& c0, f32x16& c1, f32x16& n0, f32x16& n1, bf16x8 (&pf)[2][2],
;                   f32x16 (&o)[4], f32x16& negm, float& mrun, float& lrun, const bf16x8 (&qf)[4]) {
;     ...
;     if (__builtin_expect(need, 0)) {
; #pragma unroll
;         for (int d = 0; d < 4; ++d)
; #pragma unroll
;             for (int r = 0; r < 16; ++r) o[d][r] *= sc;
;     }
.LBB0_470:
	v_pk_mul_f32 v[62:63], v[62:63], v[194:195] op_sel_hi:[1,0]
	v_pk_mul_f32 v[60:61], v[60:61], v[194:195] op_sel_hi:[1,0]
	v_pk_mul_f32 v[58:59], v[58:59], v[194:195] op_sel_hi:[1,0]
	v_pk_mul_f32 v[56:57], v[56:57], v[194:195] op_sel_hi:[1,0]
	v_pk_mul_f32 v[54:55], v[54:55], v[194:195] op_sel_hi:[1,0]
	v_pk_mul_f32 v[52:53], v[52:53], v[194:195] op_sel_hi:[1,0]
	v_pk_mul_f32 v[50:51], v[50:51], v[194:195] op_sel_hi:[1,0]
	v_pk_mul_f32 v[48:49], v[48:49], v[194:195] op_sel_hi:[1,0]
	v_pk_mul_f32 v[46:47], v[194:195], v[46:47] op_sel_hi:[0,1]
	v_pk_mul_f32 v[44:45], v[194:195], v[44:45] op_sel_hi:[0,1]
	v_pk_mul_f32 v[42:43], v[194:195], v[42:43] op_sel_hi:[0,1]
	v_pk_mul_f32 v[40:41], v[194:195], v[40:41] op_sel_hi:[0,1]
	v_pk_mul_f32 v[38:39], v[194:195], v[38:39] op_sel_hi:[0,1]
	v_pk_mul_f32 v[36:37], v[194:195], v[36:37] op_sel_hi:[0,1]
	v_pk_mul_f32 v[34:35], v[194:195], v[34:35] op_sel_hi:[0,1]
	v_pk_mul_f32 v[32:33], v[194:195], v[32:33] op_sel_hi:[0,1]
	v_pk_mul_f32 v[30:31], v[194:195], v[30:31] op_sel_hi:[0,1]
	v_pk_mul_f32 v[28:29], v[194:195], v[28:29] op_sel_hi:[0,1]
	v_pk_mul_f32 v[26:27], v[194:195], v[26:27] op_sel_hi:[0,1]
	v_pk_mul_f32 v[24:25], v[194:195], v[24:25] op_sel_hi:[0,1]
	v_pk_mul_f32 v[22:23], v[194:195], v[22:23] op_sel_hi:[0,1]
	v_pk_mul_f32 v[20:21], v[194:195], v[20:21] op_sel_hi:[0,1]
	v_pk_mul_f32 v[18:19], v[194:195], v[18:19] op_sel_hi:[0,1]
	v_pk_mul_f32 v[16:17], v[194:195], v[16:17] op_sel_hi:[0,1]
	v_pk_mul_f32 v[14:15], v[194:195], v[14:15] op_sel_hi:[0,1]
	v_pk_mul_f32 v[12:13], v[194:195], v[12:13] op_sel_hi:[0,1]
	v_pk_mul_f32 v[10:11], v[194:195], v[10:11] op_sel_hi:[0,1]
	v_pk_mul_f32 v[8:9], v[194:195], v[8:9] op_sel_hi:[0,1]
	v_pk_mul_f32 v[6:7], v[194:195], v[6:7] op_sel_hi:[0,1]
	v_pk_mul_f32 v[4:5], v[194:195], v[4:5] op_sel_hi:[0,1]
	v_pk_mul_f32 v[2:3], v[194:195], v[2:3] op_sel_hi:[0,1]
	v_pk_mul_f32 v[0:1], v[194:195], v[0:1] op_sel_hi:[0,1]
	v_mov_b32_e32 v194, 1.0
	s_branch .LBB0_465
	.p2align 6
